# EpiF32 loop: single 16-MFMA phases pre-issue 2 MFMAs (merged pair phases keep 4), rest as v20
# baseline (speedup 1.0000x reference)
; #define PG8_STAGE(bufoff, gbase, voff) do { _Pragma("unroll") for (int _i = 0; _i < 2; ++_i) \
;         __builtin_amdgcn_global_load_lds((const unsigned*)((const char*)(gbase) + (voff)[_i]), (LAS unsigned*)(lds + (bufoff) + ldsw + _i * 8192), 16, 0, 0); } while (0)
; #define PG8_LDA(dst, b, h) do { _Pragma("unroll") for (int m = 0; m < 4; ++m) _Pragma("unroll") for (int k = 0; k < 2; ++k) dst[m][k] = *(const LAS bf16x8*)(lds + PG8_SA(b, h) + aoff + m * 2048 + k * 1024); } while (0)
; #define PG8_LDB(dst, b, h) do { _Pragma("unroll") for (int n = 0; n < 2; ++n) _Pragma("unroll") for (int k = 0; k < 2; ++k) dst[n][k] = *(const LAS bf16x8*)(lds + PG8_SB(b, h) + boff + n * 2048 + k * 1024); } while (0)
; #define PG8_MMA(ai, bj, At, Bt) do { __builtin_amdgcn_s_setprio(1); _Pragma("unroll") for (int m = 0; m < 4; ++m) _Pragma("unroll") for (int n = 0; n < 2; ++n) _Pragma("unroll") for (int k = 0; k < 2; ++k) \
;         acc[ai][bj][m][n] = __builtin_amdgcn_mfma_f32_16x16x32_bf16(Bt[n][k], At[m][k], acc[ai][bj][m][n], 0, 0, 0); __builtin_amdgcn_s_setprio(0); } while (0)
; #define PG8_WAIT_V(n) asm volatile("s_waitcnt vmcnt(" #n ")" ::: "memory")
; #define PG8_WAIT_L(n) asm volatile("s_waitcnt lgkmcnt(" #n ")" ::: "memory")
; #define PG8_BAR __builtin_amdgcn_s_barrier()
; #define PG8_SCHED __builtin_amdgcn_sched_barrier(0)
; template <class Epi>
; __device__ __forceinline__ void gemm_phase(LAS unsigned char* lds, const Gemm g, const Sched& S, const Epi& E) {
;     ...
;             PG8_LDB(B0, 0, 0); PG8_SCHED; PG8_LDA(At, 0, 0); PG8_STAGE(PG8_SA(1, 1), a1 + hstepA, voffA);
;             PG8_WAIT_L(8); PG8_BAR; PG8_WAIT_L(0); PG8_MMA(0, 0, At, B0); PG8_BAR; PG8_SCHED;
;             PG8_LDB(B1, 0, 1); PG8_STAGE(PG8_SB(0, 0), b2, voffB);
;             PG8_BAR; PG8_WAIT_L(0); PG8_MMA(0, 1, At, B1); PG8_BAR;
;             PG8_LDA(At, 0, 1); PG8_STAGE(PG8_SA(0, 0), a2, voffA);
;             PG8_BAR; PG8_WAIT_L(0); PG8_MMA(1, 0, At, B0); PG8_BAR; PG8_SCHED;
;             PG8_STAGE(PG8_SB(0, 1), b2 + hstepB, voffB);
;             PG8_WAIT_V(6); PG8_BAR; PG8_MMA(1, 1, At, B1); PG8_BAR;
.Lresync_y_719:
.LBB0_719:
	s_add_i32 s14, s4, 2
	s_add_u32 s15, s0, 0x80
	s_addc_u32 s5, s1, 0
	s_add_i32 s8, 0, 0x10000
	v_add_u32_e32 v118, s8, v217
	ds_read_b128 v[106:109], v118
	ds_read_b128 v[110:113], v118 offset:1024
	ds_read_b128 v[114:117], v118 offset:2048
	ds_read_b128 v[118:121], v118 offset:3072
	s_cmp_eq_u32 s48, s4
	s_cselect_b32 s4, s59, s15
	s_cselect_b32 s5, s57, s5
	s_cselect_b32 s95, vcc_lo, s35
	s_cselect_b32 s94, vcc_hi, s34
	v_lshl_add_u64 v[154:155], s[0:1], 0, v[202:203]
	s_add_i32 m0, s52, 0xc000
	ds_read_b128 v[122:125], v235
	ds_read_b128 v[126:129], v235 offset:1024
	ds_read_b128 v[130:133], v235 offset:2048
	ds_read_b128 v[134:137], v235 offset:3072
	ds_read_b128 v[138:141], v235 offset:4096
	ds_read_b128 v[142:145], v235 offset:5120
	ds_read_b128 v[146:149], v235 offset:6144
	ds_read_b128 v[150:153], v235 offset:7168
	global_load_lds_dwordx4 v[154:155], off
	v_lshl_add_u64 v[154:155], s[0:1], 0, v[204:205]
	s_add_i32 m0, s52, 0xe000
	s_nop 0
	global_load_lds_dwordx4 v[154:155], off
	s_waitcnt lgkmcnt(8)
	s_waitcnt lgkmcnt(0)
	v_mfma_f32_16x16x32_bf16 v[162:165], v[114:117], v[130:133], v[162:165]
	v_mfma_f32_16x16x32_bf16 v[94:97], v[106:109], v[138:141], v[94:97]
	s_barrier
	s_waitcnt lgkmcnt(0)
	s_setprio 1
	s_waitcnt lgkmcnt(0)
	v_mfma_f32_16x16x32_bf16 v[90:93], v[114:117], v[138:141], v[90:93]
	v_mfma_f32_16x16x32_bf16 v[78:81], v[106:109], v[146:149], v[78:81]
	v_mfma_f32_16x16x32_bf16 v[74:77], v[114:117], v[146:149], v[74:77]
	v_mfma_f32_16x16x32_bf16 v[154:157], v[106:109], v[122:125], v[190:193]
	v_mfma_f32_16x16x32_bf16 v[158:161], v[114:117], v[122:125], v[186:189]
	v_mfma_f32_16x16x32_bf16 v[166:169], v[106:109], v[130:133], v[174:177]
	v_mfma_f32_16x16x32_bf16 v[162:165], v[118:121], v[134:137], v[162:165]
	v_mfma_f32_16x16x32_bf16 v[94:97], v[110:113], v[142:145], v[94:97]
	v_mfma_f32_16x16x32_bf16 v[90:93], v[118:121], v[142:145], v[90:93]
	v_mfma_f32_16x16x32_bf16 v[78:81], v[110:113], v[150:153], v[78:81]
	v_mfma_f32_16x16x32_bf16 v[74:77], v[118:121], v[150:153], v[74:77]
	v_mfma_f32_16x16x32_bf16 v[154:157], v[110:113], v[126:129], v[154:157]
	v_mfma_f32_16x16x32_bf16 v[158:161], v[118:121], v[126:129], v[158:161]
	v_mfma_f32_16x16x32_bf16 v[166:169], v[110:113], v[134:137], v[166:169]
	s_setprio 0
	s_barrier
	s_add_i32 s9, 0, 0x14000
	s_add_i32 s8, s8, s43
	v_add_u32_e32 v190, s9, v217
	v_lshl_add_u64 v[210:211], s[94:95], 0, v[0:1]
	s_mov_b32 m0, s8
	ds_read_b128 v[170:173], v190
	ds_read_b128 v[174:177], v190 offset:1024
	ds_read_b128 v[186:189], v190 offset:2048
	ds_read_b128 v[190:193], v190 offset:3072
	global_load_lds_dwordx4 v[210:211], off
	v_lshl_add_u64 v[212:213], s[94:95], 0, v[200:201]
	s_add_i32 m0, s8, 0x2000
	s_nop 0
	global_load_lds_dwordx4 v[212:213], off
	s_waitcnt lgkmcnt(0)
	v_mfma_f32_16x16x32_bf16 v[182:185], v[170:173], v[122:125], v[182:185]
	v_mfma_f32_16x16x32_bf16 v[102:105], v[170:173], v[130:133], v[102:105]
	s_barrier
	s_waitcnt lgkmcnt(0)
	s_setprio 1
	s_waitcnt lgkmcnt(0)
	v_mfma_f32_16x16x32_bf16 v[98:101], v[186:189], v[130:133], v[98:101]
	v_mfma_f32_16x16x32_bf16 v[86:89], v[170:173], v[138:141], v[86:89]
	v_mfma_f32_16x16x32_bf16 v[82:85], v[186:189], v[138:141], v[82:85]
	v_mfma_f32_16x16x32_bf16 v[70:73], v[170:173], v[146:149], v[70:73]
	v_mfma_f32_16x16x32_bf16 v[66:69], v[186:189], v[146:149], v[66:69]
	v_mfma_f32_16x16x32_bf16 v[182:185], v[174:177], v[126:129], v[182:185]
	v_mfma_f32_16x16x32_bf16 v[122:125], v[186:189], v[122:125], v[178:181]
	v_mfma_f32_16x16x32_bf16 v[102:105], v[174:177], v[134:137], v[102:105]
	v_mfma_f32_16x16x32_bf16 v[98:101], v[190:193], v[134:137], v[98:101]
	v_mfma_f32_16x16x32_bf16 v[86:89], v[174:177], v[142:145], v[86:89]
	v_mfma_f32_16x16x32_bf16 v[82:85], v[190:193], v[142:145], v[82:85]
	v_mfma_f32_16x16x32_bf16 v[70:73], v[174:177], v[150:153], v[70:73]
	v_mfma_f32_16x16x32_bf16 v[66:69], v[190:193], v[150:153], v[66:69]
	v_mfma_f32_16x16x32_bf16 v[122:125], v[190:193], v[126:129], v[122:125]
	s_setprio 0
	s_mov_b32 m0, s52
	v_lshl_add_u64 v[214:215], s[4:5], 0, v[196:197]
	s_barrier
	ds_read_b128 v[126:129], v235 offset:16384
	ds_read_b128 v[130:133], v235 offset:17408
	ds_read_b128 v[134:137], v235 offset:18432
	ds_read_b128 v[138:141], v235 offset:19456
	ds_read_b128 v[142:145], v235 offset:20480
	ds_read_b128 v[146:149], v235 offset:21504
	ds_read_b128 v[150:153], v235 offset:22528
	ds_read_b128 v[178:181], v235 offset:23552
	global_load_lds_dwordx4 v[214:215], off
	v_lshl_add_u64 v[222:223], s[4:5], 0, v[198:199]
	s_mov_b32 m0, s53
	s_nop 0
	global_load_lds_dwordx4 v[222:223], off
	s_add_u32 s94, s94, s76
	s_addc_u32 s95, s95, s77
	s_add_i32 s8, s9, s43
	v_lshl_add_u64 v[224:225], s[94:95], 0, v[0:1]
	s_mov_b32 m0, s8
	v_lshl_add_u64 v[226:227], s[94:95], 0, v[200:201]
	global_load_lds_dwordx4 v[224:225], off
	s_add_i32 m0, s8, 0x2000
	s_nop 0
	global_load_lds_dwordx4 v[226:227], off
	s_waitcnt vmcnt(6)
	s_waitcnt lgkmcnt(0)
	v_mfma_f32_16x16x32_bf16 v[62:65], v[106:109], v[126:129], v[62:65]
	v_mfma_f32_16x16x32_bf16 v[58:61], v[114:117], v[126:129], v[58:61]
	v_mfma_f32_16x16x32_bf16 v[46:49], v[106:109], v[134:137], v[46:49]
	v_mfma_f32_16x16x32_bf16 v[42:45], v[114:117], v[134:137], v[42:45]
	s_barrier
; #define PG8_STAGE(bufoff, gbase, voff) do { _Pragma("unroll") for (int _i = 0; _i < 2; ++_i) \
;         __builtin_amdgcn_global_load_lds((const unsigned*)((const char*)(gbase) + (voff)[_i]), (LAS unsigned*)(lds + (bufoff) + ldsw + _i * 8192), 16, 0, 0); } while (0)
; #define PG8_LDA(dst, b, h) do { _Pragma("unroll") for (int m = 0; m < 4; ++m) _Pragma("unroll") for (int k = 0; k < 2; ++k) dst[m][k] = *(const LAS bf16x8*)(lds + PG8_SA(b, h) + aoff + m * 2048 + k * 1024); } while (0)
; #define PG8_LDB(dst, b, h) do { _Pragma("unroll") for (int n = 0; n < 2; ++n) _Pragma("unroll") for (int k = 0; k < 2; ++k) dst[n][k] = *(const LAS bf16x8*)(lds + PG8_SB(b, h) + boff + n * 2048 + k * 1024); } while (0)
; #define PG8_MMA(ai, bj, At, Bt) do { __builtin_amdgcn_s_setprio(1); _Pragma("unroll") for (int m = 0; m < 4; ++m) _Pragma("unroll") for (int n = 0; n < 2; ++n) _Pragma("unroll") for (int k = 0; k < 2; ++k) \
;         acc[ai][bj][m][n] = __builtin_amdgcn_mfma_f32_16x16x32_bf16(Bt[n][k], At[m][k], acc[ai][bj][m][n], 0, 0, 0); __builtin_amdgcn_s_setprio(0); } while (0)
; #define PG8_WAIT_V(n) asm volatile("s_waitcnt vmcnt(" #n ")" ::: "memory")
; #define PG8_WAIT_L(n) asm volatile("s_waitcnt lgkmcnt(" #n ")" ::: "memory")
; #define PG8_BAR __builtin_amdgcn_s_barrier()
; #define PG8_SCHED __builtin_amdgcn_sched_barrier(0)
; template <class Epi>
; __device__ __forceinline__ void gemm_phase(LAS unsigned char* lds, const Gemm g, const Sched& S, const Epi& E) {
;     ...
;             PG8_WAIT_V(6); PG8_BAR; PG8_MMA(1, 1, At, B1); PG8_BAR;
;             PG8_LDB(B0, 1, 0); PG8_SCHED; PG8_LDA(At, 1, 0); PG8_STAGE(PG8_SA(0, 1), a2 + hstepA, voffA);
;             PG8_WAIT_L(8); PG8_BAR; PG8_WAIT_L(0); PG8_MMA(0, 0, At, B0); PG8_BAR; PG8_SCHED;
;             PG8_LDB(B1, 1, 1); PG8_STAGE(PG8_SB(1, 0), b3, voffB);
;             PG8_BAR; PG8_WAIT_L(0); PG8_MMA(0, 1, At, B1); PG8_BAR;
	s_setprio 1
	v_mfma_f32_16x16x32_bf16 v[30:33], v[106:109], v[142:145], v[30:33]
	v_mfma_f32_16x16x32_bf16 v[26:29], v[114:117], v[142:145], v[26:29]
	v_mfma_f32_16x16x32_bf16 v[14:17], v[106:109], v[150:153], v[14:17]
	v_mfma_f32_16x16x32_bf16 v[10:13], v[114:117], v[150:153], v[10:13]
	v_mfma_f32_16x16x32_bf16 v[62:65], v[110:113], v[130:133], v[62:65]
	v_mfma_f32_16x16x32_bf16 v[58:61], v[118:121], v[130:133], v[58:61]
	v_mfma_f32_16x16x32_bf16 v[46:49], v[110:113], v[138:141], v[46:49]
	v_mfma_f32_16x16x32_bf16 v[42:45], v[118:121], v[138:141], v[42:45]
	v_mfma_f32_16x16x32_bf16 v[30:33], v[110:113], v[146:149], v[30:33]
	v_mfma_f32_16x16x32_bf16 v[26:29], v[118:121], v[146:149], v[26:29]
	v_mfma_f32_16x16x32_bf16 v[14:17], v[110:113], v[178:181], v[14:17]
	v_mfma_f32_16x16x32_bf16 v[10:13], v[118:121], v[178:181], v[10:13]
	v_mfma_f32_16x16x32_bf16 v[54:57], v[170:173], v[126:129], v[54:57]
	v_mfma_f32_16x16x32_bf16 v[50:53], v[186:189], v[126:129], v[50:53]
	v_mfma_f32_16x16x32_bf16 v[38:41], v[170:173], v[134:137], v[38:41]
	v_mfma_f32_16x16x32_bf16 v[34:37], v[186:189], v[134:137], v[34:37]
	v_mfma_f32_16x16x32_bf16 v[22:25], v[170:173], v[142:145], v[22:25]
	v_mfma_f32_16x16x32_bf16 v[18:21], v[186:189], v[142:145], v[18:21]
	v_mfma_f32_16x16x32_bf16 v[6:9], v[170:173], v[150:153], v[6:9]
	v_mfma_f32_16x16x32_bf16 v[2:5], v[186:189], v[150:153], v[2:5]
	v_mfma_f32_16x16x32_bf16 v[54:57], v[174:177], v[130:133], v[54:57]
	v_mfma_f32_16x16x32_bf16 v[50:53], v[190:193], v[130:133], v[50:53]
	v_mfma_f32_16x16x32_bf16 v[38:41], v[174:177], v[138:141], v[38:41]
	v_mfma_f32_16x16x32_bf16 v[34:37], v[190:193], v[138:141], v[34:37]
	v_mfma_f32_16x16x32_bf16 v[22:25], v[174:177], v[146:149], v[22:25]
	v_mfma_f32_16x16x32_bf16 v[18:21], v[190:193], v[146:149], v[18:21]
	v_mfma_f32_16x16x32_bf16 v[6:9], v[174:177], v[178:181], v[6:9]
	v_mfma_f32_16x16x32_bf16 v[2:5], v[190:193], v[178:181], v[2:5]
	s_setprio 0
	s_add_i32 s8, 0, 0x18000
	v_add_u32_e32 v118, s8, v217
	s_barrier
	ds_read_b128 v[106:109], v118
	ds_read_b128 v[110:113], v118 offset:1024
	ds_read_b128 v[114:117], v118 offset:2048
	ds_read_b128 v[118:121], v118 offset:3072
	s_add_u32 s4, s4, s40
	s_addc_u32 s5, s5, s41
	s_mov_b32 m0, s56
	v_lshl_add_u64 v[174:175], s[4:5], 0, v[196:197]
	ds_read_b128 v[126:129], v235 offset:32768
	ds_read_b128 v[130:133], v235 offset:33792
	ds_read_b128 v[134:137], v235 offset:34816
	ds_read_b128 v[138:141], v235 offset:35840
	ds_read_b128 v[142:145], v235 offset:36864
	ds_read_b128 v[146:149], v235 offset:37888
	ds_read_b128 v[150:153], v235 offset:38912
	ds_read_b128 v[170:173], v235 offset:39936
	global_load_lds_dwordx4 v[174:175], off
	v_lshl_add_u64 v[174:175], s[4:5], 0, v[198:199]
	s_mov_b32 m0, s67
	s_nop 0
	global_load_lds_dwordx4 v[174:175], off
	s_waitcnt lgkmcnt(8)
	s_waitcnt lgkmcnt(0)
	v_mfma_f32_16x16x32_bf16 v[154:157], v[106:109], v[126:129], v[154:157]
	v_mfma_f32_16x16x32_bf16 v[190:193], v[110:113], v[130:133], v[154:157]
	s_barrier
	s_waitcnt lgkmcnt(0)
	s_setprio 1
	s_waitcnt lgkmcnt(0)
	v_mfma_f32_16x16x32_bf16 v[154:157], v[114:117], v[126:129], v[158:161]
	v_mfma_f32_16x16x32_bf16 v[186:189], v[118:121], v[130:133], v[154:157]
	v_mfma_f32_16x16x32_bf16 v[154:157], v[106:109], v[134:137], v[166:169]
	v_mfma_f32_16x16x32_bf16 v[174:177], v[110:113], v[138:141], v[154:157]
	v_mfma_f32_16x16x32_bf16 v[154:157], v[114:117], v[134:137], v[162:165]
	v_mfma_f32_16x16x32_bf16 v[94:97], v[106:109], v[142:145], v[94:97]
	v_mfma_f32_16x16x32_bf16 v[90:93], v[114:117], v[142:145], v[90:93]
	v_mfma_f32_16x16x32_bf16 v[78:81], v[106:109], v[150:153], v[78:81]
	v_mfma_f32_16x16x32_bf16 v[74:77], v[114:117], v[150:153], v[74:77]
	v_mfma_f32_16x16x32_bf16 v[162:165], v[118:121], v[138:141], v[154:157]
	v_mfma_f32_16x16x32_bf16 v[94:97], v[110:113], v[146:149], v[94:97]
	v_mfma_f32_16x16x32_bf16 v[90:93], v[118:121], v[146:149], v[90:93]
	v_mfma_f32_16x16x32_bf16 v[78:81], v[110:113], v[170:173], v[78:81]
	v_mfma_f32_16x16x32_bf16 v[74:77], v[118:121], v[170:173], v[74:77]
	s_setprio 0
	s_barrier
	s_add_i32 s4, 0, 0x1c000
	v_add_u32_e32 v178, s4, v217
	s_add_i32 s5, s8, s43
	ds_read_b128 v[154:157], v178
	ds_read_b128 v[158:161], v178 offset:1024
	ds_read_b128 v[166:169], v178 offset:2048
	ds_read_b128 v[206:209], v178 offset:3072
	v_lshl_add_u64 v[178:179], v[210:211], 0, s[60:61]
	s_mov_b32 m0, s5
	s_nop 0
	global_load_lds_dwordx4 v[178:179], off
	v_lshl_add_u64 v[178:179], v[212:213], 0, s[60:61]
	s_add_i32 m0, s5, 0x2000
	s_nop 0
	global_load_lds_dwordx4 v[178:179], off
	s_waitcnt lgkmcnt(0)
	v_mfma_f32_16x16x32_bf16 v[178:181], v[154:157], v[126:129], v[182:185]
	v_mfma_f32_16x16x32_bf16 v[122:125], v[166:169], v[126:129], v[122:125]
	s_barrier
; #define PG8_STAGE(bufoff, gbase, voff) do { _Pragma("unroll") for (int _i = 0; _i < 2; ++_i) \
;         __builtin_amdgcn_global_load_lds((const unsigned*)((const char*)(gbase) + (voff)[_i]), (LAS unsigned*)(lds + (bufoff) + ldsw + _i * 8192), 16, 0, 0); } while (0)
; #define PG8_LDA(dst, b, h) do { _Pragma("unroll") for (int m = 0; m < 4; ++m) _Pragma("unroll") for (int k = 0; k < 2; ++k) dst[m][k] = *(const LAS bf16x8*)(lds + PG8_SA(b, h) + aoff + m * 2048 + k * 1024); } while (0)
; #define PG8_MMA(ai, bj, At, Bt) do { __builtin_amdgcn_s_setprio(1); _Pragma("unroll") for (int m = 0; m < 4; ++m) _Pragma("unroll") for (int n = 0; n < 2; ++n) _Pragma("unroll") for (int k = 0; k < 2; ++k) \
;         acc[ai][bj][m][n] = __builtin_amdgcn_mfma_f32_16x16x32_bf16(Bt[n][k], At[m][k], acc[ai][bj][m][n], 0, 0, 0); __builtin_amdgcn_s_setprio(0); } while (0)
; #define PG8_WAIT_V(n) asm volatile("s_waitcnt vmcnt(" #n ")" ::: "memory")
; #define PG8_WAIT_L(n) asm volatile("s_waitcnt lgkmcnt(" #n ")" ::: "memory")
; #define PG8_BAR __builtin_amdgcn_s_barrier()
; #define PG8_SCHED __builtin_amdgcn_sched_barrier(0)
; template <class Epi>
; __device__ __forceinline__ void gemm_phase(LAS unsigned char* lds, const Gemm g, const Sched& S, const Epi& E) {
;     ...
;             PG8_BAR; PG8_WAIT_L(0); PG8_MMA(0, 1, At, B1); PG8_BAR;
;             PG8_LDA(At, 1, 1); PG8_STAGE(PG8_SA(1, 0), a3, voffA);
;             PG8_BAR; PG8_WAIT_L(0); PG8_MMA(1, 0, At, B0); PG8_BAR; PG8_SCHED;
;             PG8_STAGE(PG8_SB(1, 1), b3 + hstepB, voffB);
;             PG8_WAIT_V(6); PG8_BAR; PG8_MMA(1, 1, At, B1); PG8_BAR;
;         }
;         E(acc, cur, wr, wc, fr, fq, pre);
;         if (!has_next) break;
	s_waitcnt lgkmcnt(0)
	s_setprio 1
	s_waitcnt lgkmcnt(0)
	v_mfma_f32_16x16x32_bf16 v[102:105], v[154:157], v[134:137], v[102:105]
	v_mfma_f32_16x16x32_bf16 v[98:101], v[166:169], v[134:137], v[98:101]
	v_mfma_f32_16x16x32_bf16 v[86:89], v[154:157], v[142:145], v[86:89]
	v_mfma_f32_16x16x32_bf16 v[82:85], v[166:169], v[142:145], v[82:85]
	v_mfma_f32_16x16x32_bf16 v[70:73], v[154:157], v[150:153], v[70:73]
	v_mfma_f32_16x16x32_bf16 v[66:69], v[166:169], v[150:153], v[66:69]
	v_mfma_f32_16x16x32_bf16 v[182:185], v[158:161], v[130:133], v[178:181]
	v_mfma_f32_16x16x32_bf16 v[178:181], v[206:209], v[130:133], v[122:125]
	v_mfma_f32_16x16x32_bf16 v[102:105], v[158:161], v[138:141], v[102:105]
	v_mfma_f32_16x16x32_bf16 v[98:101], v[206:209], v[138:141], v[98:101]
	v_mfma_f32_16x16x32_bf16 v[86:89], v[158:161], v[146:149], v[86:89]
	v_mfma_f32_16x16x32_bf16 v[82:85], v[206:209], v[146:149], v[82:85]
	v_mfma_f32_16x16x32_bf16 v[70:73], v[158:161], v[170:173], v[70:73]
	v_mfma_f32_16x16x32_bf16 v[66:69], v[206:209], v[170:173], v[66:69]
	s_setprio 0
	s_mov_b32 m0, s51
	v_lshl_add_u64 v[170:171], v[214:215], 0, s[60:61]
	s_barrier
	ds_read_b128 v[122:125], v235 offset:49152
	ds_read_b128 v[126:129], v235 offset:50176
	ds_read_b128 v[130:133], v235 offset:51200
	ds_read_b128 v[134:137], v235 offset:52224
	ds_read_b128 v[138:141], v235 offset:53248
	ds_read_b128 v[142:145], v235 offset:54272
	ds_read_b128 v[146:149], v235 offset:55296
	ds_read_b128 v[150:153], v235 offset:56320
	global_load_lds_dwordx4 v[170:171], off
	v_lshl_add_u64 v[170:171], v[222:223], 0, s[60:61]
	s_mov_b32 m0, s2
	s_nop 0
	global_load_lds_dwordx4 v[170:171], off
	s_add_i32 s4, s4, s43
	v_lshl_add_u64 v[170:171], v[224:225], 0, s[60:61]
	s_mov_b32 m0, s4
	s_nop 0
	global_load_lds_dwordx4 v[170:171], off
	v_lshl_add_u64 v[170:171], v[226:227], 0, s[60:61]
	s_add_i32 m0, s4, 0x2000
	s_nop 0
	global_load_lds_dwordx4 v[170:171], off
	s_waitcnt vmcnt(6)
	s_waitcnt lgkmcnt(0)
	v_mfma_f32_16x16x32_bf16 v[62:65], v[106:109], v[122:125], v[62:65]
	v_mfma_f32_16x16x32_bf16 v[58:61], v[114:117], v[122:125], v[58:61]
	v_mfma_f32_16x16x32_bf16 v[46:49], v[106:109], v[130:133], v[46:49]
	v_mfma_f32_16x16x32_bf16 v[42:45], v[114:117], v[130:133], v[42:45]
	s_barrier
	s_setprio 1
	v_mfma_f32_16x16x32_bf16 v[30:33], v[106:109], v[138:141], v[30:33]
	v_mfma_f32_16x16x32_bf16 v[26:29], v[114:117], v[138:141], v[26:29]
	v_mfma_f32_16x16x32_bf16 v[14:17], v[106:109], v[146:149], v[14:17]
	v_mfma_f32_16x16x32_bf16 v[10:13], v[114:117], v[146:149], v[10:13]
	v_mfma_f32_16x16x32_bf16 v[62:65], v[110:113], v[126:129], v[62:65]
	v_mfma_f32_16x16x32_bf16 v[58:61], v[118:121], v[126:129], v[58:61]
	v_mfma_f32_16x16x32_bf16 v[46:49], v[110:113], v[134:137], v[46:49]
	v_mfma_f32_16x16x32_bf16 v[42:45], v[118:121], v[134:137], v[42:45]
	v_mfma_f32_16x16x32_bf16 v[30:33], v[110:113], v[142:145], v[30:33]
	v_mfma_f32_16x16x32_bf16 v[26:29], v[118:121], v[142:145], v[26:29]
	v_mfma_f32_16x16x32_bf16 v[14:17], v[110:113], v[150:153], v[14:17]
	v_mfma_f32_16x16x32_bf16 v[10:13], v[118:121], v[150:153], v[10:13]
	v_mfma_f32_16x16x32_bf16 v[54:57], v[154:157], v[122:125], v[54:57]
	v_mfma_f32_16x16x32_bf16 v[50:53], v[166:169], v[122:125], v[50:53]
	v_mfma_f32_16x16x32_bf16 v[38:41], v[154:157], v[130:133], v[38:41]
	v_mfma_f32_16x16x32_bf16 v[34:37], v[166:169], v[130:133], v[34:37]
	v_mfma_f32_16x16x32_bf16 v[22:25], v[154:157], v[138:141], v[22:25]
	v_mfma_f32_16x16x32_bf16 v[18:21], v[166:169], v[138:141], v[18:21]
	v_mfma_f32_16x16x32_bf16 v[6:9], v[154:157], v[146:149], v[6:9]
	v_mfma_f32_16x16x32_bf16 v[2:5], v[166:169], v[146:149], v[2:5]
	v_mfma_f32_16x16x32_bf16 v[54:57], v[158:161], v[126:129], v[54:57]
	v_mfma_f32_16x16x32_bf16 v[50:53], v[206:209], v[126:129], v[50:53]
	v_mfma_f32_16x16x32_bf16 v[38:41], v[158:161], v[134:137], v[38:41]
	v_mfma_f32_16x16x32_bf16 v[34:37], v[206:209], v[134:137], v[34:37]
	v_mfma_f32_16x16x32_bf16 v[22:25], v[158:161], v[142:145], v[22:25]
	v_mfma_f32_16x16x32_bf16 v[18:21], v[206:209], v[142:145], v[18:21]
	v_mfma_f32_16x16x32_bf16 v[6:9], v[158:161], v[150:153], v[6:9]
	v_mfma_f32_16x16x32_bf16 v[2:5], v[206:209], v[150:153], v[2:5]
	s_setprio 0
	s_add_u32 s0, s0, 0x100
	s_addc_u32 s1, s1, 0
	s_add_u32 s34, s34, 0x100
	s_addc_u32 s35, s35, 0
	s_cmp_ge_u32 s14, s73
	s_mov_b32 s4, s14
	s_barrier
	s_cbranch_scc0 .LBB0_719
	v_readfirstlane_b32 s98, v219
	s_nop 1
	s_bitcmp1_b32 s98, 8
	s_cbranch_scc1 .Lresync_x_719
	s_barrier
